# residual epilogue (FFN_OUT/MIX_OUT): all 32 loads + fmas first, the 32 row stores afterwards (load waits no longer behind store acks)
# baseline (speedup 1.0000x reference)
.LBB0_456:
	s_lshl_b64 s[8:9], s[8:9], 2
	s_add_u32 s8, s89, s8
	s_addc_u32 s9, s52, s9
	v_lshl_or_b32 v168, s58, 8, v177
	v_lshlrev_b32_e32 v168, 2, v168
	s_lshl_b32 s5, s23, 8
	v_add_u32_e32 v128, s5, v172
	s_cmp_lg_u32 s22, 0
	s_cbranch_scc1 .Lresid_split
	global_load_dwordx4 v[142:145], v168, s[8:9]
	global_load_dwordx4 v[138:141], v168, s[8:9] offset:16
	global_load_dwordx4 v[134:137], v168, s[8:9] offset:512
	global_load_dwordx4 v[130:133], v168, s[8:9] offset:528
	v_lshl_add_u32 v128, v128, 12, v168
	v_mov_b32_e32 v170, v128
	global_load_dwordx4 v[198:201], v170, s[24:25]
	global_load_dwordx4 v[202:205], v170, s[24:25] offset:16
	global_load_dwordx4 v[206:209], v170, s[24:25] offset:512
	global_load_dwordx4 v[210:213], v170, s[24:25] offset:528
	v_add_u32_e32 v170, 0x10000, v128
	global_load_dwordx4 v[214:217], v170, s[24:25]
	global_load_dwordx4 v[218:221], v170, s[24:25] offset:16
	global_load_dwordx4 v[222:225], v170, s[24:25] offset:512
	global_load_dwordx4 v[226:229], v170, s[24:25] offset:528
	v_add_u32_e32 v170, 0x20000, v128
	global_load_dwordx4 v[238:241], v170, s[24:25]
	global_load_dwordx4 v[242:245], v170, s[24:25] offset:16
	global_load_dwordx4 v[246:249], v170, s[24:25] offset:512
	global_load_dwordx4 v[250:253], v170, s[24:25] offset:528
	v_add_u32_e32 v170, 0x30000, v128
	global_load_dwordx4 v[158:161], v170, s[24:25]
	global_load_dwordx4 v[162:165], v170, s[24:25] offset:16
	s_waitcnt vmcnt(13)
	v_pk_mul_f32 v[142:143], s[28:29], v[142:143]
	v_pk_mul_f32 v[144:145], s[28:29], v[144:145]
	v_pk_mul_f32 v[138:139], s[28:29], v[138:139]
	v_pk_mul_f32 v[140:141], s[28:29], v[140:141]
	v_pk_mul_f32 v[134:135], s[28:29], v[134:135]
	v_pk_mul_f32 v[136:137], s[28:29], v[136:137]
	v_pk_mul_f32 v[130:131], s[28:29], v[130:131]
	v_pk_mul_f32 v[132:133], s[28:29], v[132:133]
	v_pk_fma_f32 v[124:125], v[124:125], v[142:143], v[198:199]
	v_pk_fma_f32 v[126:127], v[126:127], v[144:145], v[200:201]
	global_load_dwordx4 v[198:201], v170, s[24:25] offset:512
	s_waitcnt vmcnt(13)
	v_pk_fma_f32 v[120:121], v[120:121], v[138:139], v[202:203]
	v_pk_fma_f32 v[122:123], v[122:123], v[140:141], v[204:205]
	global_load_dwordx4 v[202:205], v170, s[24:25] offset:528
	s_waitcnt vmcnt(13)
	v_pk_fma_f32 v[116:117], v[116:117], v[134:135], v[206:207]
	v_pk_fma_f32 v[118:119], v[118:119], v[136:137], v[208:209]
	v_add_u32_e32 v170, 0x80000, v128
	global_load_dwordx4 v[206:209], v170, s[24:25]
	s_waitcnt vmcnt(13)
	v_pk_fma_f32 v[112:113], v[112:113], v[130:131], v[210:211]
	v_pk_fma_f32 v[114:115], v[114:115], v[132:133], v[212:213]
	global_load_dwordx4 v[210:213], v170, s[24:25] offset:16
	s_waitcnt vmcnt(13)
	v_pk_fma_f32 v[108:109], v[108:109], v[142:143], v[214:215]
	v_pk_fma_f32 v[110:111], v[110:111], v[144:145], v[216:217]
	global_load_dwordx4 v[214:217], v170, s[24:25] offset:512
	s_waitcnt vmcnt(13)
	v_pk_fma_f32 v[104:105], v[104:105], v[138:139], v[218:219]
	v_pk_fma_f32 v[106:107], v[106:107], v[140:141], v[220:221]
	global_load_dwordx4 v[218:221], v170, s[24:25] offset:528
	s_waitcnt vmcnt(13)
	v_pk_fma_f32 v[100:101], v[100:101], v[134:135], v[222:223]
	v_pk_fma_f32 v[102:103], v[102:103], v[136:137], v[224:225]
	v_add_u32_e32 v170, 0x90000, v128
	global_load_dwordx4 v[222:225], v170, s[24:25]
	s_waitcnt vmcnt(13)
	v_pk_fma_f32 v[96:97], v[96:97], v[130:131], v[226:227]
	v_pk_fma_f32 v[98:99], v[98:99], v[132:133], v[228:229]
	global_load_dwordx4 v[226:229], v170, s[24:25] offset:16
	s_waitcnt vmcnt(13)
	v_pk_fma_f32 v[92:93], v[92:93], v[142:143], v[238:239]
	v_pk_fma_f32 v[94:95], v[94:95], v[144:145], v[240:241]
	global_load_dwordx4 v[238:241], v170, s[24:25] offset:512
	s_waitcnt vmcnt(13)
	v_pk_fma_f32 v[88:89], v[88:89], v[138:139], v[242:243]
	v_pk_fma_f32 v[90:91], v[90:91], v[140:141], v[244:245]
	global_load_dwordx4 v[242:245], v170, s[24:25] offset:528
	s_waitcnt vmcnt(13)
	v_pk_fma_f32 v[84:85], v[84:85], v[134:135], v[246:247]
	v_pk_fma_f32 v[86:87], v[86:87], v[136:137], v[248:249]
	v_add_u32_e32 v170, 0xa0000, v128
	global_load_dwordx4 v[246:249], v170, s[24:25]
	s_waitcnt vmcnt(13)
	v_pk_fma_f32 v[80:81], v[80:81], v[130:131], v[250:251]
	v_pk_fma_f32 v[82:83], v[82:83], v[132:133], v[252:253]
	global_load_dwordx4 v[250:253], v170, s[24:25] offset:16
	s_waitcnt vmcnt(13)
	v_pk_fma_f32 v[76:77], v[76:77], v[142:143], v[158:159]
	v_pk_fma_f32 v[78:79], v[78:79], v[144:145], v[160:161]
	global_load_dwordx4 v[158:161], v170, s[24:25] offset:512
	s_waitcnt vmcnt(13)
	v_pk_fma_f32 v[72:73], v[72:73], v[138:139], v[162:163]
	v_pk_fma_f32 v[74:75], v[74:75], v[140:141], v[164:165]
	global_load_dwordx4 v[162:165], v170, s[24:25] offset:528
	s_waitcnt vmcnt(13)
	v_pk_fma_f32 v[68:69], v[68:69], v[134:135], v[198:199]
	v_pk_fma_f32 v[70:71], v[70:71], v[136:137], v[200:201]
	v_add_u32_e32 v170, 0xb0000, v128
	global_load_dwordx4 v[198:201], v170, s[24:25]
	s_waitcnt vmcnt(13)
	v_pk_fma_f32 v[64:65], v[64:65], v[130:131], v[202:203]
	v_pk_fma_f32 v[66:67], v[66:67], v[132:133], v[204:205]
	global_load_dwordx4 v[202:205], v170, s[24:25] offset:16
	s_waitcnt vmcnt(13)
	v_pk_fma_f32 v[60:61], v[60:61], v[142:143], v[206:207]
	v_pk_fma_f32 v[62:63], v[62:63], v[144:145], v[208:209]
	global_load_dwordx4 v[206:209], v170, s[24:25] offset:512
	s_waitcnt vmcnt(13)
	v_pk_fma_f32 v[56:57], v[56:57], v[138:139], v[210:211]
	v_pk_fma_f32 v[58:59], v[58:59], v[140:141], v[212:213]
	global_load_dwordx4 v[210:213], v170, s[24:25] offset:528
	s_waitcnt vmcnt(13)
	v_pk_fma_f32 v[52:53], v[52:53], v[134:135], v[214:215]
	v_pk_fma_f32 v[54:55], v[54:55], v[136:137], v[216:217]
	s_waitcnt vmcnt(12)
	v_pk_fma_f32 v[48:49], v[48:49], v[130:131], v[218:219]
	v_pk_fma_f32 v[50:51], v[50:51], v[132:133], v[220:221]
	s_waitcnt vmcnt(11)
	v_pk_fma_f32 v[44:45], v[44:45], v[142:143], v[222:223]
	v_pk_fma_f32 v[46:47], v[46:47], v[144:145], v[224:225]
	s_waitcnt vmcnt(10)
	v_pk_fma_f32 v[40:41], v[40:41], v[138:139], v[226:227]
	v_pk_fma_f32 v[42:43], v[42:43], v[140:141], v[228:229]
	s_waitcnt vmcnt(9)
	v_pk_fma_f32 v[36:37], v[36:37], v[134:135], v[238:239]
	v_pk_fma_f32 v[38:39], v[38:39], v[136:137], v[240:241]
	s_waitcnt vmcnt(8)
	v_pk_fma_f32 v[32:33], v[32:33], v[130:131], v[242:243]
	v_pk_fma_f32 v[34:35], v[34:35], v[132:133], v[244:245]
	s_waitcnt vmcnt(7)
	v_pk_fma_f32 v[28:29], v[28:29], v[142:143], v[246:247]
	v_pk_fma_f32 v[30:31], v[30:31], v[144:145], v[248:249]
	s_waitcnt vmcnt(6)
	v_pk_fma_f32 v[24:25], v[24:25], v[138:139], v[250:251]
	v_pk_fma_f32 v[26:27], v[26:27], v[140:141], v[252:253]
	s_waitcnt vmcnt(5)
	v_pk_fma_f32 v[20:21], v[20:21], v[134:135], v[158:159]
	v_pk_fma_f32 v[22:23], v[22:23], v[136:137], v[160:161]
	s_waitcnt vmcnt(4)
	v_pk_fma_f32 v[16:17], v[16:17], v[130:131], v[162:163]
	v_pk_fma_f32 v[18:19], v[18:19], v[132:133], v[164:165]
	s_waitcnt vmcnt(3)
	v_pk_fma_f32 v[12:13], v[12:13], v[142:143], v[198:199]
	v_pk_fma_f32 v[14:15], v[14:15], v[144:145], v[200:201]
	s_waitcnt vmcnt(2)
	v_pk_fma_f32 v[8:9], v[8:9], v[138:139], v[202:203]
	v_pk_fma_f32 v[10:11], v[10:11], v[140:141], v[204:205]
	s_waitcnt vmcnt(1)
	v_pk_fma_f32 v[4:5], v[4:5], v[134:135], v[206:207]
	v_pk_fma_f32 v[6:7], v[6:7], v[136:137], v[208:209]
	s_waitcnt vmcnt(0)
	v_pk_fma_f32 v[0:1], v[0:1], v[130:131], v[210:211]
	v_pk_fma_f32 v[2:3], v[2:3], v[132:133], v[212:213]
	v_mov_b32_e32 v171, v128
	global_store_dwordx4 v171, v[124:127], s[24:25]
	global_store_dwordx4 v171, v[120:123], s[24:25] offset:16
	global_store_dwordx4 v171, v[116:119], s[24:25] offset:512
	global_store_dwordx4 v171, v[112:115], s[24:25] offset:528
	v_add_u32_e32 v171, 0x10000, v128
	global_store_dwordx4 v171, v[108:111], s[24:25]
	global_store_dwordx4 v171, v[104:107], s[24:25] offset:16
	global_store_dwordx4 v171, v[100:103], s[24:25] offset:512
	global_store_dwordx4 v171, v[96:99], s[24:25] offset:528
	v_add_u32_e32 v171, 0x20000, v128
	global_store_dwordx4 v171, v[92:95], s[24:25]
	global_store_dwordx4 v171, v[88:91], s[24:25] offset:16
	global_store_dwordx4 v171, v[84:87], s[24:25] offset:512
	global_store_dwordx4 v171, v[80:83], s[24:25] offset:528
	v_add_u32_e32 v171, 0x30000, v128
	global_store_dwordx4 v171, v[76:79], s[24:25]
	global_store_dwordx4 v171, v[72:75], s[24:25] offset:16
	global_store_dwordx4 v171, v[68:71], s[24:25] offset:512
	global_store_dwordx4 v171, v[64:67], s[24:25] offset:528
	v_add_u32_e32 v171, 0x80000, v128
	global_store_dwordx4 v171, v[60:63], s[24:25]
	global_store_dwordx4 v171, v[56:59], s[24:25] offset:16
	global_store_dwordx4 v171, v[52:55], s[24:25] offset:512
	global_store_dwordx4 v171, v[48:51], s[24:25] offset:528
	v_add_u32_e32 v171, 0x90000, v128
	global_store_dwordx4 v171, v[44:47], s[24:25]
	global_store_dwordx4 v171, v[40:43], s[24:25] offset:16
	global_store_dwordx4 v171, v[36:39], s[24:25] offset:512
	global_store_dwordx4 v171, v[32:35], s[24:25] offset:528
	v_add_u32_e32 v171, 0xa0000, v128
	global_store_dwordx4 v171, v[28:31], s[24:25]
	global_store_dwordx4 v171, v[24:27], s[24:25] offset:16
	global_store_dwordx4 v171, v[20:23], s[24:25] offset:512
	global_store_dwordx4 v171, v[16:19], s[24:25] offset:528
	v_add_u32_e32 v171, 0xb0000, v128
	global_store_dwordx4 v171, v[12:15], s[24:25]
	global_store_dwordx4 v171, v[8:11], s[24:25] offset:16
	global_store_dwordx4 v171, v[4:7], s[24:25] offset:512
	global_store_dwordx4 v171, v[0:3], s[24:25] offset:528
	s_branch .Lresid_done
